# windowed-attention inner loop: row max as a v_max3 tree without canonicalising v_max x,x; prev/next-block masking as one compare per score against (query - key0)
# speedup vs baseline: 1.0085x; 1.0085x over previous
; __device__ __forceinline__ void swa_item(const KPD& kp, int l, int item, unsigned char* lds, int tid, int lane, int wave) {
;     ...
;         for (int h2 = 0; h2 < 2 * ntl; ++h2) {
;             const int slot = h2 >> 1, half = h2 & 1, mode = tile_mode(ta + slot);
;             const bf16* Ktt = Kt + slot * 18432; const bf16* Vss = Vs + slot * 18432;
;             if ((mode == 1 && half == 0 && wave >= 4) || (mode == 2 && half == 1 && wave <= 3)) continue;
;             f32x4 S[3][4];
; #pragma unroll
;             for (int ct = 0; ct < 4; ++ct) {
; #pragma unroll
;                 for (int hh = 0; hh < 3; ++hh) S[hh][ct] = (f32x4){0.f, 0.f, 0.f, 0.f};
; #pragma unroll
;                 for (int ks = 0; ks < 2; ++ks) { const bf16x8 kf = *(const bf16x8*)(Ktt + (64 * half + 16 * ct + fr) * 72 + 32 * ks + 8 * fq);
; #pragma unroll
;                     for (int hh = 0; hh < 3; ++hh) S[hh][ct] = __builtin_amdgcn_mfma_f32_16x16x32_bf16(kf, qf[hh][ks], S[hh][ct], 0, 0, 0); } }
;             if (mode != 0) {
;                 const int qi = 16 * wave + fr;
; #pragma unroll
;                 for (int ct = 0; ct < 4; ++ct)
; #pragma unroll
;                     for (int r = 0; r < 4; ++r) { const int key = 64 * half + 16 * ct + 4 * fq + r;
;                         const bool bad = (mode == 1) ? (key < qi) : (key > qi);
;                         if (bad) { S[0][ct][r] = -1e30f; S[1][ct][r] = -1e30f; S[2][ct][r] = -1e30f; } }
;             }
.LBB0_383:
	s_lshr_b32 s27, s26, 1
	s_and_b32 s28, s26, 1
	s_add_i32 s12, s27, s24
	s_cmp_eq_u32 s12, 0
	s_cselect_b64 s[4:5], -1, 0
	s_and_b64 s[4:5], s[8:9], s[4:5]
	s_cmp_eq_u32 s28, 0
	s_cselect_b64 s[30:31], -1, 0
	s_and_b64 s[30:31], s[0:1], s[30:31]
	s_and_b64 s[30:31], s[30:31], s[4:5]
	s_and_b64 vcc, exec, s[30:31]
	s_cbranch_vccnz .LBB0_382
	s_cmp_eq_u32 s12, s17
	s_cselect_b64 s[12:13], -1, 0
	s_and_b64 s[12:13], s[10:11], s[12:13]
	s_xor_b64 s[30:31], s[4:5], -1
	s_cmp_lg_u32 s28, 0
	s_cselect_b64 s[34:35], -1, 0
	s_and_b64 s[30:31], s[34:35], s[30:31]
	s_and_b64 s[30:31], s[2:3], s[30:31]
	s_and_b64 s[30:31], s[12:13], s[30:31]
	s_and_b64 vcc, exec, s[30:31]
	s_cbranch_vccnz .LBB0_382
	s_mul_i32 s29, s27, 0x4800
	s_lshl_b32 s27, s28, 6
	v_or_b32_e32 v38, s27, v37
	s_lshl_b32 s28, s29, 1
	v_mul_u32_u24_e32 v38, 0x90, v38
	v_add3_u32 v38, v178, s28, v38
	ds_read_b128 v[114:117], v38
	ds_read_b128 v[118:121], v38 offset:64
	s_or_b64 s[12:13], s[4:5], s[12:13]
	s_waitcnt lgkmcnt(1)
	v_mfma_f32_16x16x32_bf16 v[122:125], v[114:117], v[2:5], 0
	s_andn2_b64 vcc, exec, s[12:13]
	v_mfma_f32_16x16x32_bf16 v[126:129], v[114:117], v[10:13], 0
	v_mfma_f32_16x16x32_bf16 v[114:117], v[114:117], v[18:21], 0
	s_waitcnt lgkmcnt(0)
	v_mfma_f32_16x16x32_bf16 v[146:149], v[118:121], v[6:9], v[122:125]
	v_mfma_f32_16x16x32_bf16 v[150:153], v[118:121], v[14:17], v[126:129]
	v_mfma_f32_16x16x32_bf16 v[126:129], v[118:121], v[22:25], v[114:117]
	s_nop 3
	ds_read_b128 v[114:117], v38 offset:2304
	ds_read_b128 v[118:121], v38 offset:2368
	s_waitcnt lgkmcnt(1)
	v_mfma_f32_16x16x32_bf16 v[122:125], v[114:117], v[2:5], 0
	v_mfma_f32_16x16x32_bf16 v[130:133], v[114:117], v[10:13], 0
	v_mfma_f32_16x16x32_bf16 v[114:117], v[114:117], v[18:21], 0
	s_waitcnt lgkmcnt(0)
	v_mfma_f32_16x16x32_bf16 v[142:145], v[118:121], v[6:9], v[122:125]
	v_mfma_f32_16x16x32_bf16 v[158:161], v[118:121], v[14:17], v[130:133]
	v_mfma_f32_16x16x32_bf16 v[114:117], v[118:121], v[22:25], v[114:117]
	ds_read_b128 v[118:121], v38 offset:4608
	s_nop 0
	ds_read_b128 v[122:125], v38 offset:4672
	s_waitcnt lgkmcnt(1)
	v_mfma_f32_16x16x32_bf16 v[130:133], v[118:121], v[2:5], 0
	v_mfma_f32_16x16x32_bf16 v[134:137], v[118:121], v[10:13], 0
	v_mfma_f32_16x16x32_bf16 v[118:121], v[118:121], v[18:21], 0
	s_waitcnt lgkmcnt(0)
	v_mfma_f32_16x16x32_bf16 v[138:141], v[122:125], v[6:9], v[130:133]
	v_mfma_f32_16x16x32_bf16 v[130:133], v[122:125], v[14:17], v[134:137]
	v_mfma_f32_16x16x32_bf16 v[118:121], v[122:125], v[22:25], v[118:121]
	ds_read_b128 v[122:125], v38 offset:6912
	ds_read_b128 v[186:189], v38 offset:6976
	s_waitcnt lgkmcnt(1)
	v_mfma_f32_16x16x32_bf16 v[134:137], v[122:125], v[2:5], 0
	v_mfma_f32_16x16x32_bf16 v[154:157], v[122:125], v[10:13], 0
	v_mfma_f32_16x16x32_bf16 v[122:125], v[122:125], v[18:21], 0
	s_waitcnt lgkmcnt(0)
	v_mfma_f32_16x16x32_bf16 v[134:137], v[186:189], v[6:9], v[134:137]
	v_mfma_f32_16x16x32_bf16 v[154:157], v[186:189], v[14:17], v[154:157]
	v_mfma_f32_16x16x32_bf16 v[122:125], v[186:189], v[22:25], v[122:125]
	s_cbranch_vccnz .LBB0_387
	v_or_b32_e32 v38, s27, v36
	v_mov_b32_e32 v186, s58
	v_mov_b32_e32 v188, s58
	v_mov_b32_e32 v190, s58
	v_sub_u32_e32 v39, v174, v38
	s_and_b64 vcc, exec, s[4:5]
	s_cbranch_vccz .Lswa_mask_next
	v_cmp_lt_i32_e64 s[30:31], 0, v39
	v_cmp_lt_i32_e64 s[34:35], 1, v39
	v_cmp_lt_i32_e64 s[36:37], 2, v39
	v_cndmask_b32_e64 v126, v126, v190, s[30:31]
	v_cndmask_b32_e64 v150, v150, v188, s[30:31]
	v_cndmask_b32_e64 v146, v146, v186, s[30:31]
	v_cmp_lt_i32_e64 s[40:41], 3, v39
	v_cndmask_b32_e64 v127, v127, v224, s[34:35]
	v_cndmask_b32_e64 v151, v151, v224, s[34:35]
	v_cndmask_b32_e64 v147, v147, v224, s[34:35]
	v_cmp_lt_i32_e64 s[30:31], 16, v39
	v_cndmask_b32_e64 v128, v128, v224, s[36:37]
	v_cndmask_b32_e64 v152, v152, v224, s[36:37]
	v_cndmask_b32_e64 v148, v148, v224, s[36:37]
	v_cmp_lt_i32_e64 s[34:35], 17, v39
	v_cndmask_b32_e64 v129, v129, v224, s[40:41]
	v_cndmask_b32_e64 v153, v153, v224, s[40:41]
	v_cndmask_b32_e64 v149, v149, v224, s[40:41]
	v_cmp_lt_i32_e64 s[36:37], 18, v39
	v_cndmask_b32_e64 v114, v114, v190, s[30:31]
	v_cndmask_b32_e64 v158, v158, v188, s[30:31]
	v_cndmask_b32_e64 v142, v142, v186, s[30:31]
	v_cmp_lt_i32_e64 s[40:41], 19, v39
	v_cndmask_b32_e64 v115, v115, v224, s[34:35]
	v_cndmask_b32_e64 v159, v159, v224, s[34:35]
	v_cndmask_b32_e64 v143, v143, v224, s[34:35]
	v_cmp_lt_i32_e64 s[30:31], 32, v39
	v_cndmask_b32_e64 v116, v116, v224, s[36:37]
	v_cndmask_b32_e64 v160, v160, v224, s[36:37]
	v_cndmask_b32_e64 v144, v144, v224, s[36:37]
	v_cmp_lt_i32_e64 s[34:35], 33, v39
	v_cndmask_b32_e64 v117, v117, v224, s[40:41]
	v_cndmask_b32_e64 v161, v161, v224, s[40:41]
	v_cndmask_b32_e64 v145, v145, v224, s[40:41]
	v_cmp_lt_i32_e64 s[36:37], 34, v39
	v_cndmask_b32_e64 v118, v118, v190, s[30:31]
	v_cndmask_b32_e64 v130, v130, v188, s[30:31]
	v_cndmask_b32_e64 v138, v138, v186, s[30:31]
	v_cmp_lt_i32_e64 s[40:41], 35, v39
	v_cndmask_b32_e64 v119, v119, v224, s[34:35]
	v_cndmask_b32_e64 v131, v131, v224, s[34:35]
	v_cndmask_b32_e64 v139, v139, v224, s[34:35]
	v_cmp_lt_i32_e64 s[30:31], 48, v39
	v_cndmask_b32_e64 v120, v120, v224, s[36:37]
	v_cndmask_b32_e64 v132, v132, v224, s[36:37]
	v_cndmask_b32_e64 v140, v140, v224, s[36:37]
	v_cmp_lt_i32_e64 s[34:35], 49, v39
	v_cndmask_b32_e64 v121, v121, v224, s[40:41]
	v_cndmask_b32_e64 v133, v133, v224, s[40:41]
	v_cndmask_b32_e64 v141, v141, v224, s[40:41]
	v_cmp_lt_i32_e64 s[36:37], 50, v39
	v_cndmask_b32_e64 v122, v122, v190, s[30:31]
	v_cndmask_b32_e64 v154, v154, v188, s[30:31]
	v_cndmask_b32_e64 v134, v134, v186, s[30:31]
	v_cmp_lt_i32_e64 s[40:41], 51, v39
	v_cndmask_b32_e64 v123, v123, v224, s[34:35]
	v_cndmask_b32_e64 v155, v155, v224, s[34:35]
	v_cndmask_b32_e64 v135, v135, v224, s[34:35]
	v_cndmask_b32_e64 v124, v124, v224, s[36:37]
	v_cndmask_b32_e64 v156, v156, v224, s[36:37]
	v_cndmask_b32_e64 v136, v136, v224, s[36:37]
	v_cndmask_b32_e64 v125, v125, v224, s[40:41]
	v_cndmask_b32_e64 v157, v157, v224, s[40:41]
	v_cndmask_b32_e64 v137, v137, v224, s[40:41]
	s_branch .LBB0_387
; __device__ __forceinline__ float xor16_32_max(float v) { float a = v, b = v; swap16(a, b); v = fmaxf(a, b); a = v; b = v; swap32(a, b); return fmaxf(a, b); }
; __device__ __forceinline__ void swa_item(const KPD& kp, int l, int item, unsigned char* lds, int tid, int lane, int wave) {
;     ...
;                     for (int r = 0; r < 4; ++r) { const int key = 64 * half + 16 * ct + 4 * fq + r;
;                         const bool bad = (mode == 1) ? (key < qi) : (key > qi);
;                         if (bad) { S[0][ct][r] = -1e30f; S[1][ct][r] = -1e30f; S[2][ct][r] = -1e30f; } }
;             }
;             bf16x8 pf[3][2];
; #pragma unroll
;             for (int hh = 0; hh < 3; ++hh) {
;                 float mx = fmaxf(fmaxf(S[hh][0][0], S[hh][0][1]), fmaxf(S[hh][0][2], S[hh][0][3]));
; #pragma unroll
;                 for (int ct = 1; ct < 4; ++ct) mx = fmaxf(mx, fmaxf(fmaxf(S[hh][ct][0], S[hh][ct][1]), fmaxf(S[hh][ct][2], S[hh][ct][3])));
;                 mx = pg8::xor16_32_max(mx);
;                 float mnew = mrow[hh];
;                 const bool resc = __builtin_amdgcn_ballot_w64(mx > mrow[hh] + 8.0f) != 0ull;
;                 if (resc) { mnew = fmaxf(mrow[hh], mx); const float alpha = __builtin_amdgcn_exp2f(mrow[hh] - mnew); lrow[hh] *= alpha;
; #pragma unroll
;                     for (int dt = 0; dt < 4; ++dt) O[hh][dt] *= alpha; }
.Lswa_mask_next:
	v_cmp_gt_i32_e64 s[30:31], 0, v39
	v_cmp_gt_i32_e64 s[34:35], 1, v39
	v_cmp_gt_i32_e64 s[36:37], 2, v39
	v_cndmask_b32_e64 v126, v126, v190, s[30:31]
	v_cndmask_b32_e64 v150, v150, v188, s[30:31]
	v_cndmask_b32_e64 v146, v146, v186, s[30:31]
	v_cmp_gt_i32_e64 s[40:41], 3, v39
	v_cndmask_b32_e64 v127, v127, v224, s[34:35]
	v_cndmask_b32_e64 v151, v151, v224, s[34:35]
	v_cndmask_b32_e64 v147, v147, v224, s[34:35]
	v_cmp_gt_i32_e64 s[30:31], 16, v39
	v_cndmask_b32_e64 v128, v128, v224, s[36:37]
	v_cndmask_b32_e64 v152, v152, v224, s[36:37]
	v_cndmask_b32_e64 v148, v148, v224, s[36:37]
	v_cmp_gt_i32_e64 s[34:35], 17, v39
	v_cndmask_b32_e64 v129, v129, v224, s[40:41]
	v_cndmask_b32_e64 v153, v153, v224, s[40:41]
	v_cndmask_b32_e64 v149, v149, v224, s[40:41]
	v_cmp_gt_i32_e64 s[36:37], 18, v39
	v_cndmask_b32_e64 v114, v114, v190, s[30:31]
	v_cndmask_b32_e64 v158, v158, v188, s[30:31]
	v_cndmask_b32_e64 v142, v142, v186, s[30:31]
	v_cmp_gt_i32_e64 s[40:41], 19, v39
	v_cndmask_b32_e64 v115, v115, v224, s[34:35]
	v_cndmask_b32_e64 v159, v159, v224, s[34:35]
	v_cndmask_b32_e64 v143, v143, v224, s[34:35]
	v_cmp_gt_i32_e64 s[30:31], 32, v39
	v_cndmask_b32_e64 v116, v116, v224, s[36:37]
	v_cndmask_b32_e64 v160, v160, v224, s[36:37]
	v_cndmask_b32_e64 v144, v144, v224, s[36:37]
	v_cmp_gt_i32_e64 s[34:35], 33, v39
	v_cndmask_b32_e64 v117, v117, v224, s[40:41]
	v_cndmask_b32_e64 v161, v161, v224, s[40:41]
	v_cndmask_b32_e64 v145, v145, v224, s[40:41]
	v_cmp_gt_i32_e64 s[36:37], 34, v39
	v_cndmask_b32_e64 v118, v118, v190, s[30:31]
	v_cndmask_b32_e64 v130, v130, v188, s[30:31]
	v_cndmask_b32_e64 v138, v138, v186, s[30:31]
	v_cmp_gt_i32_e64 s[40:41], 35, v39
	v_cndmask_b32_e64 v119, v119, v224, s[34:35]
	v_cndmask_b32_e64 v131, v131, v224, s[34:35]
	v_cndmask_b32_e64 v139, v139, v224, s[34:35]
	v_cmp_gt_i32_e64 s[30:31], 48, v39
	v_cndmask_b32_e64 v120, v120, v224, s[36:37]
	v_cndmask_b32_e64 v132, v132, v224, s[36:37]
	v_cndmask_b32_e64 v140, v140, v224, s[36:37]
	v_cmp_gt_i32_e64 s[34:35], 49, v39
	v_cndmask_b32_e64 v121, v121, v224, s[40:41]
	v_cndmask_b32_e64 v133, v133, v224, s[40:41]
	v_cndmask_b32_e64 v141, v141, v224, s[40:41]
	v_cmp_gt_i32_e64 s[36:37], 50, v39
	v_cndmask_b32_e64 v122, v122, v190, s[30:31]
	v_cndmask_b32_e64 v154, v154, v188, s[30:31]
	v_cndmask_b32_e64 v134, v134, v186, s[30:31]
	v_cmp_gt_i32_e64 s[40:41], 51, v39
	v_cndmask_b32_e64 v123, v123, v224, s[34:35]
	v_cndmask_b32_e64 v155, v155, v224, s[34:35]
	v_cndmask_b32_e64 v135, v135, v224, s[34:35]
	v_cndmask_b32_e64 v124, v124, v224, s[36:37]
	v_cndmask_b32_e64 v156, v156, v224, s[36:37]
	v_cndmask_b32_e64 v136, v136, v224, s[36:37]
	v_cndmask_b32_e64 v125, v125, v224, s[40:41]
	v_cndmask_b32_e64 v157, v157, v224, s[40:41]
	v_cndmask_b32_e64 v137, v137, v224, s[40:41]
.LBB0_387:
	v_max3_f32 v38, v138, v139, v140
	v_max3_f32 v39, v141, v142, v143
	v_max3_f32 v40, v144, v145, v146
	v_max3_f32 v41, v147, v148, v149
	v_max3_f32 v38, v38, v39, v40
	s_nop 1
	v_max3_f32 v38, v38, v41, v134
	v_max3_f32 v38, v38, v135, v136
	v_max_f32_e32 v38, v38, v137
	v_mov_b32_e32 v39, v38
	s_nop 1
	v_permlane16_swap_b32 v39, v38
	s_nop 0
	v_max_f32_e32 v38, v39, v38
	v_mov_b32_e32 v39, v38
	s_nop 1
	v_permlane32_swap_b32 v39, v38
	s_nop 0
	v_max_f32_e32 v186, v39, v38
	v_add_f32_e32 v38, 0x41000000, v181
	v_cmp_gt_f32_e32 vcc, v186, v38
	s_cbranch_vccz .LBB0_389
	v_max_f32_e32 v38, v186, v186
	v_max_f32_e32 v39, v181, v181
	v_max_f32_e32 v38, v39, v38
	v_sub_f32_e32 v39, v181, v38
	v_exp_f32_e32 v186, v39
	v_mov_b32_e32 v181, v38
	v_mul_f32_e32 v167, v167, v186
	v_pk_mul_f32 v[108:109], v[108:109], v[186:187] op_sel_hi:[1,0]
	v_pk_mul_f32 v[106:107], v[106:107], v[186:187] op_sel_hi:[1,0]
	v_pk_mul_f32 v[112:113], v[112:113], v[186:187] op_sel_hi:[1,0]
	v_pk_mul_f32 v[110:111], v[110:111], v[186:187] op_sel_hi:[1,0]
	v_pk_mul_f32 v[104:105], v[104:105], v[186:187] op_sel_hi:[1,0]
	v_pk_mul_f32 v[102:103], v[102:103], v[186:187] op_sel_hi:[1,0]
	v_pk_mul_f32 v[100:101], v[100:101], v[186:187] op_sel_hi:[1,0]
	v_pk_mul_f32 v[98:99], v[98:99], v[186:187] op_sel_hi:[1,0]
.LBB0_389:
	v_max3_f32 v38, v130, v131, v132
	v_max3_f32 v39, v133, v150, v151
	v_max3_f32 v40, v152, v153, v158
	v_max3_f32 v41, v159, v160, v161
	v_max3_f32 v38, v38, v39, v40
	s_nop 1
	v_max3_f32 v38, v38, v41, v154
	v_max3_f32 v38, v38, v155, v156
	v_max_f32_e32 v38, v38, v157
	v_mov_b32_e32 v39, v38
	s_nop 1
	v_permlane16_swap_b32 v39, v38
	s_nop 0
	v_max_f32_e32 v38, v39, v38
	v_mov_b32_e32 v39, v38
	s_nop 1
	v_permlane32_swap_b32 v39, v38
	s_nop 0
	v_max_f32_e32 v186, v39, v38
	v_add_f32_e32 v38, 0x41000000, v173
	v_cmp_gt_f32_e32 vcc, v186, v38
	s_cbranch_vccz .LBB0_391
	v_max_f32_e32 v38, v186, v186
	v_max_f32_e32 v39, v173, v173
	v_max_f32_e32 v38, v39, v38
	v_sub_f32_e32 v39, v173, v38
	v_exp_f32_e32 v186, v39
	v_mov_b32_e32 v173, v38
	v_mul_f32_e32 v165, v165, v186
	v_pk_mul_f32 v[92:93], v[92:93], v[186:187] op_sel_hi:[1,0]
	v_pk_mul_f32 v[90:91], v[90:91], v[186:187] op_sel_hi:[1,0]
	v_pk_mul_f32 v[96:97], v[96:97], v[186:187] op_sel_hi:[1,0]
	v_pk_mul_f32 v[94:95], v[94:95], v[186:187] op_sel_hi:[1,0]
	v_pk_mul_f32 v[88:89], v[88:89], v[186:187] op_sel_hi:[1,0]
	v_pk_mul_f32 v[86:87], v[86:87], v[186:187] op_sel_hi:[1,0]
	v_pk_mul_f32 v[84:85], v[84:85], v[186:187] op_sel_hi:[1,0]
	v_pk_mul_f32 v[82:83], v[82:83], v[186:187] op_sel_hi:[1,0]
.LBB0_391:
	v_max3_f32 v38, v114, v115, v116
	v_max3_f32 v39, v117, v118, v119
	v_max3_f32 v40, v120, v121, v126
	v_max3_f32 v41, v127, v128, v129
	v_max3_f32 v38, v38, v39, v40
	s_nop 1
	v_max3_f32 v38, v38, v41, v122
	v_max3_f32 v38, v38, v123, v124
	v_max_f32_e32 v38, v38, v125
	v_mov_b32_e32 v39, v38
	s_nop 1
	v_permlane16_swap_b32 v39, v38
	s_nop 0
	v_max_f32_e32 v38, v39, v38
	v_mov_b32_e32 v39, v38
	s_nop 1
	v_permlane32_swap_b32 v39, v38
	s_nop 0
	v_max_f32_e32 v186, v39, v38
	v_add_f32_e32 v38, 0x41000000, v172
	v_cmp_gt_f32_e32 vcc, v186, v38
	s_cbranch_vccz .LBB0_381
	v_max_f32_e32 v38, v186, v186
	v_max_f32_e32 v39, v172, v172
	v_max_f32_e32 v38, v39, v38
	v_sub_f32_e32 v39, v172, v38
	v_exp_f32_e32 v172, v39
	s_nop 0
	v_mul_f32_e32 v163, v163, v172
	v_pk_mul_f32 v[76:77], v[76:77], v[172:173] op_sel_hi:[1,0]
	v_pk_mul_f32 v[74:75], v[74:75], v[172:173] op_sel_hi:[1,0]
	v_pk_mul_f32 v[80:81], v[80:81], v[172:173] op_sel_hi:[1,0]
	v_pk_mul_f32 v[78:79], v[78:79], v[172:173] op_sel_hi:[1,0]
	v_pk_mul_f32 v[68:69], v[68:69], v[172:173] op_sel_hi:[1,0]
	v_pk_mul_f32 v[66:67], v[66:67], v[172:173] op_sel_hi:[1,0]
	v_pk_mul_f32 v[72:73], v[72:73], v[172:173] op_sel_hi:[1,0]
	v_pk_mul_f32 v[70:71], v[70:71], v[172:173] op_sel_hi:[1,0]
	v_mov_b32_e32 v172, v38
	s_branch .LBB0_381
